# v34 + branch-GEMM: deleted the never-read second-B-slot LDS-DMA staging (20 sites), counted waits re-derived (8->6, 16->14, prologue 6->4)
# speedup vs baseline: 1.0100x; 1.0100x over previous
; template <class Epi, class Sched, bool HALFN = false>
; __device__ __forceinline__ void gemm_phase(LAS unsigned char* lds, const Gemm g, const Sched& S, const Epi& E, int wave_s) {
;     const int lane = lane_id_v(), wid = wave_s, tid = wid * 64 + lane, wr = wid >> 2, wc = wid & 3, fr = lane & 15, fq = lane >> 4;
;     const int K = g.K, nt = K / BK;
;     unsigned voffA[2], voffB[2];
; #pragma unroll
;     for (int i = 0; i < 2; ++i) { int R, C; stage_rc(tid * 16 + i * 8192, R, C); const int Rb = (R & ~31) + perm32(R & 31);
;         voffA[i] = (unsigned)(R * K + C) * 2u; voffB[i] = (unsigned)(Rb * K + C) * 2u; }
;     const size_t kstep = (size_t)(BK * 2);
;     const size_t hstep = (size_t)HALF * K * 2;
;     const size_t tstep = 2 * hstep;
;     const unsigned ldsw = (unsigned)wid * 1024u;
;     ...
;     Unit cur, nxt; int ui = 0;
;     if (!S.next(0, cur)) return;
;     if constexpr (Epi::PREFETCH) E.prefetch(cur, wid, lane);
;     f32x4 acc[2][2][4][2];
; #pragma unroll
;     for (int a = 0; a < 2; ++a)
; #pragma unroll
;         for (int b = 0; b < 2; ++b)
; #pragma unroll
;             for (int m = 0; m < 4; ++m)
; #pragma unroll
;                 for (int n = 0; n < 2; ++n) acc[a][b][m][n] = (f32x4){0.f, 0.f, 0.f, 0.f};
;     f32x4 yacc[2][4][2]; u32x4 gpre[8];
;     if constexpr (HALFN) E.gates(cur, wr, wc, lane, gpre);
;     if constexpr (HALFN) {
; #pragma unroll
;         for (int a = 0; a < 2; ++a)
; #pragma unroll
;             for (int m = 0; m < 4; ++m)
; #pragma unroll
;                 for (int n = 0; n < 2; ++n) yacc[a][m][n] = (f32x4){0.f, 0.f, 0.f, 0.f};
;     }
;     bf16x8 At[4][2], B0[2][2], B1[2][2];
;     const char* cA = (const char*)g.A + (size_t)cur.z * g.zA * 2 + (size_t)cur.pm * tstep; const char* cB = (const char*)g.Bt + (size_t)cur.z * g.zB * 2 + (size_t)cur.pn * (HALFN ? hstep : tstep);
;     const size_t bh1 = HALFN ? 0 : hstep;
;     PG8_STAGE(PG8_SB(0, 0), cB, voffB); PG8_STAGE(PG8_SB(0, 1), cB + bh1, voffB); PG8_STAGE(PG8_SA(0, 0), cA, voffA); PG8_STAGE(PG8_SA(0, 1), cA + hstep, voffA);
;     if (wr == 1) PG8_BAR;
;     __device__ __forceinline__ void gates(const Unit& u, int wr, int wc, int lane, u32x4 (&gp)[8]) const {
;         const int fr = lane & 15, fq = lane >> 4;
;         const bf16_t* gb = P + (size_t)(u.pm * 256 + wr * 64 + fr) * LDP + PC_G + u.z * 1024 + u.pn * 128 + wc * 32 + 8 * fq;
; #pragma unroll
.LBB0_880:
	s_andn2_b64 vcc, exec, s[6:7]
	s_cbranch_vccnz .LBB0_912
	s_add_u32 s2, s4, 0x3123e800
	v_readlane_b32 s6, v255, 25
	s_addc_u32 s3, s5, 0
	v_readlane_b32 s7, v255, 26
	s_mov_b32 s10, s6
	s_mul_i32 s6, s6, 0x300000
	s_add_u32 s6, s4, s6
	s_mul_hi_u32 s7, s10, 0x300000
	s_addc_u32 s7, s5, s7
	s_add_u32 s38, s6, 0x3c86000
	s_addc_u32 s39, s7, 0
	s_add_u32 s10, s4, 0xd1c6800
	s_addc_u32 s11, s5, 0
	s_lshl_b32 s41, s9, 10
	v_lshl_add_u32 v2, v1, 4, s41
	v_ashrrev_i32_e32 v3, 31, v2
	v_lshrrev_b32_e32 v3, 22, v3
	v_add_u32_e32 v3, v2, v3
	v_ashrrev_i32_e32 v3, 10, v3
	v_mul_i32_i24_e32 v4, 0x400, v3
	v_sub_u32_e32 v4, v2, v4
	v_lshrrev_b32_e32 v5, 4, v4
	v_bitop3_b32 v4, v5, v4, 32 bitop3:0x6c
	v_ashrrev_i32_e32 v6, 31, v4
	v_lshrrev_b32_e32 v6, 26, v6
	v_lshlrev_b32_e32 v5, 3, v3
	v_add_u32_e32 v6, v4, v6
	v_and_b32_e32 v5, -16, v5
	v_ashrrev_i32_e32 v7, 6, v6
	v_and_b32_e32 v6, 0xc0, v6
	v_add_u32_e32 v5, v7, v5
	v_sub_u32_e32 v4, v4, v6
	v_lshlrev_b32_e32 v3, 5, v3
	v_ashrrev_i16_sdwa v4, v201, sext(v4) dst_sel:DWORD dst_unused:UNUSED_PAD src0_sel:DWORD src1_sel:BYTE_0
	v_lshlrev_b32_e32 v6, 1, v5
	v_lshrrev_b32_e32 v8, 2, v5
	v_and_b32_e32 v7, 3, v7
	s_mov_b32 s6, 0x3fffe0
	v_and_b32_e32 v3, 32, v3
	v_bfe_i32 v4, v4, 0, 16
	v_and_b32_e32 v6, 24, v6
	v_and_b32_e32 v8, 4, v8
	v_and_or_b32 v7, v5, s6, v7
	v_or3_b32 v6, v7, v8, v6
	v_add_lshl_u32 v3, v3, v4, 1
	v_add_u32_e32 v2, 0x2000, v2
	v_lshl_add_u32 v100, v5, 10, v3
	v_lshl_add_u32 v18, v6, 10, v3
	v_ashrrev_i32_e32 v3, 31, v2
	v_lshrrev_b32_e32 v3, 22, v3
	v_add_u32_e32 v3, v2, v3
	v_ashrrev_i32_e32 v3, 10, v3
	v_mul_i32_i24_e32 v4, 0x400, v3
	v_sub_u32_e32 v2, v2, v4
	v_lshrrev_b32_e32 v4, 4, v2
	v_bitop3_b32 v2, v4, v2, 32 bitop3:0x6c
	v_ashrrev_i32_e32 v5, 31, v2
	v_lshrrev_b32_e32 v5, 26, v5
	v_add_u32_e32 v5, v2, v5
	v_ashrrev_i32_e32 v6, 6, v5
	v_and_b32_e32 v5, 0xffc0, v5
	v_sub_u32_e32 v2, v2, v5
	v_lshlrev_b32_e32 v4, 3, v3
	v_lshrrev_b16_e32 v5, 7, v2
	v_and_b32_e32 v4, -16, v4
	v_and_b32_e32 v5, 1, v5
	v_add_u32_e32 v4, v6, v4
	v_add_u16_e32 v2, v2, v5
	v_and_b32_e32 v6, 3, v6
	v_lshlrev_b32_e32 v3, 5, v3
	v_ashrrev_i16_sdwa v2, v201, sext(v2) dst_sel:DWORD dst_unused:UNUSED_PAD src0_sel:DWORD src1_sel:BYTE_0
	v_lshlrev_b32_e32 v5, 1, v4
	v_lshrrev_b32_e32 v7, 2, v4
	v_and_or_b32 v6, v4, s6, v6
	s_ashr_i32 s6, s9, 2
	v_and_b32_e32 v3, 32, v3
	v_bfe_i32 v2, v2, 0, 16
	v_and_b32_e32 v5, 24, v5
	v_and_b32_e32 v7, 4, v7
	s_lshl_b32 s7, s28, 8
	s_lshl_b32 s45, s6, 6
	v_or3_b32 v5, v6, v7, v5
	v_add_lshl_u32 v2, v3, v2, 1
	s_add_i32 s7, s7, s45
	v_lshl_add_u32 v102, v4, 10, v2
	v_lshl_add_u32 v104, v5, 10, v2
	v_and_or_b32 v4, v1, 15, s7
	v_mov_b64_e32 v[2:3], s[10:11]
	v_mad_i64_i32 v[2:3], s[12:13], v4, s40, v[2:3]
	s_lshl_b32 s12, s30, 7
	s_lshl_b32 s7, s9, 5
	s_ashr_i32 s13, s12, 31
	s_and_b32 s46, s7, 0x60
	v_ashrrev_i32_e32 v1, 1, v1
	v_lshl_add_u64 v[2:3], s[12:13], 1, v[2:3]
	s_lshl_b32 s12, s46, 1
	s_mov_b32 s13, s49
	v_and_b32_e32 v4, -8, v1
	v_lshl_add_u64 v[2:3], v[2:3], 0, s[12:13]
	v_ashrrev_i32_e32 v5, 31, v4
	v_lshl_add_u64 v[2:3], v[4:5], 1, v[2:3]
	v_add_co_u32_e32 v4, vcc, s60, v2
	s_mov_b32 s53, 0x37000
	s_nop 0
	v_addc_co_u32_e32 v5, vcc, 0, v3, vcc
	v_add_co_u32_e32 v6, vcc, s53, v2
	s_mov_b32 s66, 0x6d000
	s_nop 0
	v_addc_co_u32_e32 v7, vcc, 0, v3, vcc
	global_load_dwordx4 v[32:35], v[4:5], off offset:3584
	global_load_dwordx4 v[28:31], v[6:7], off offset:3584
	v_add_co_u32_e32 v4, vcc, s66, v2
	s_mov_b32 s71, 0xa3000
	s_nop 0
	v_addc_co_u32_e32 v5, vcc, 0, v3, vcc
	v_add_co_u32_e32 v6, vcc, s71, v2
	s_mov_b32 s7, 0x1b1000
	s_nop 0
	v_addc_co_u32_e32 v7, vcc, 0, v3, vcc
	global_load_dwordx4 v[24:27], v[4:5], off offset:3584
	global_load_dwordx4 v[20:23], v[6:7], off offset:3584
	v_add_co_u32_e32 v4, vcc, s7, v2
	s_mov_b32 s7, 0x1e7000
	s_nop 0
	v_addc_co_u32_e32 v5, vcc, 0, v3, vcc
	v_add_co_u32_e32 v6, vcc, s7, v2
	s_mov_b32 s7, 0x21d000
	s_nop 0
	v_addc_co_u32_e32 v7, vcc, 0, v3, vcc
	s_ashr_i32 s29, s28, 31
	s_ashr_i32 s31, s30, 31
	global_load_dwordx4 v[14:17], v[4:5], off offset:3584
	global_load_dwordx4 v[10:13], v[6:7], off offset:3584
	v_add_co_u32_e32 v4, vcc, s7, v2
	s_lshl_b64 s[14:15], s[28:29], 18
	s_lshl_b64 s[16:17], s[30:31], 17
	v_addc_co_u32_e32 v5, vcc, 0, v3, vcc
	s_mov_b32 s7, 0x253000
	s_add_u32 s36, s38, s16
	v_add_co_u32_e32 v2, vcc, s7, v2
	s_addc_u32 s37, s39, s17
	s_add_i32 s31, s41, 0
	v_addc_co_u32_e32 v3, vcc, 0, v3, vcc
	s_add_i32 m0, s31, 0x10000
	global_load_dwordx4 v[6:9], v[4:5], off offset:3584
	s_nop 0
	global_load_dwordx4 v[2:5], v[2:3], off offset:3584
	s_add_i32 s47, s31, 0x14000
	global_load_lds_dwordx4 v18, s[36:37]
	s_add_i32 m0, s31, 0x12000
	s_add_i32 s55, s31, 0x16000
	global_load_lds_dwordx4 v104, s[36:37]
	s_add_u32 s34, s2, s14
	s_addc_u32 s35, s3, s15
	s_add_i32 s56, s31, 0x2000
	s_mov_b32 m0, s31
	s_add_u32 s14, s34, 0x20000
	global_load_lds_dwordx4 v100, s[34:35]
	s_mov_b32 m0, s56
	s_addc_u32 s15, s35, 0
	s_add_i32 s57, s31, 0x4000
	global_load_lds_dwordx4 v102, s[34:35]
	s_mov_b32 m0, s57
	s_add_i32 s58, s31, 0x6000
	global_load_lds_dwordx4 v100, s[14:15]
	s_mov_b32 m0, s58
	v_mov_b32_e32 v105, v19
	global_load_lds_dwordx4 v102, s[14:15]
	v_mov_b32_e32 v101, v19
	v_mov_b32_e32 v103, v19
	s_cmp_eq_u32 s6, 1
	v_lshl_add_u64 v[42:43], s[36:37], 0, v[18:19]
	v_lshl_add_u64 v[40:41], s[36:37], 0, v[104:105]
	v_lshl_add_u64 v[36:37], s[34:35], 0, v[100:101]
	s_cselect_b64 s[14:15], -1, 0
	s_cmp_lg_u32 s6, 1
	v_lshl_add_u64 v[38:39], s[34:35], 0, v[102:103]
	s_cbranch_scc1 .LBB0_883
	s_barrier
; __device__ __forceinline__ int lane_id_v() { int l; asm volatile("v_mbcnt_lo_u32_b32 %0, -1, 0\n\tv_mbcnt_hi_u32_b32 %0, -1, %0" : "=v"(l)); return l; }
; #define PG8_STAGE(bufoff, gbase, voff) do { _Pragma("unroll") for (int _i = 0; _i < 2; ++_i) \
;         __builtin_amdgcn_global_load_lds((const unsigned*)((const char*)(gbase) + (voff)[_i]), (LAS unsigned*)(lds + (bufoff) + ldsw + _i * 8192), 16, 0, 0); } while (0)
; #define PG8_WAIT_V(n) asm volatile("s_waitcnt vmcnt(" #n ")" ::: "memory")
; #define PG8_BAR __builtin_amdgcn_s_barrier()
; template <class Epi, class Sched, bool HALFN = false>
; __device__ __forceinline__ void gemm_phase(LAS unsigned char* lds, const Gemm g, const Sched& S, const Epi& E, int wave_s) {
;     ...
;     if constexpr (HALFN) {
; #pragma unroll
;         for (int a = 0; a < 2; ++a)
; #pragma unroll
;             for (int m = 0; m < 4; ++m)
; #pragma unroll
;                 for (int n = 0; n < 2; ++n) yacc[a][m][n] = (f32x4){0.f, 0.f, 0.f, 0.f};
;     }
;     bf16x8 At[4][2], B0[2][2], B1[2][2];
;     const char* cA = (const char*)g.A + (size_t)cur.z * g.zA * 2 + (size_t)cur.pm * tstep; const char* cB = (const char*)g.Bt + (size_t)cur.z * g.zB * 2 + (size_t)cur.pn * (HALFN ? hstep : tstep);
;     const size_t bh1 = HALFN ? 0 : hstep;
;     PG8_STAGE(PG8_SB(0, 0), cB, voffB); PG8_STAGE(PG8_SB(0, 1), cB + bh1, voffB); PG8_STAGE(PG8_SA(0, 0), cA, voffA); PG8_STAGE(PG8_SA(0, 1), cA + hstep, voffA);
;     if (wr == 1) PG8_BAR;
;     PG8_WAIT_V(2); PG8_BAR;
;     PG8_STAGE(PG8_SB(1, 0), cB + kstep, voffB); PG8_STAGE(PG8_SA(1, 0), cA + kstep, voffA); PG8_STAGE(PG8_SB(1, 1), cB + bh1 + kstep, voffB);
;     PG8_WAIT_V(6); PG8_BAR;
;     const int l3 = lane_id_v();
;     const int aoff = lds_byte(wr * 64 + (l3 & 15), (l3 >> 4) * 8), boff = lds_byte(wc * 32 + (l3 & 15), (l3 >> 4) * 8);
;     for (;;) {
.LBB0_883:
	s_add_u32 s16, s4, 0x372fe800
	s_addc_u32 s17, s5, 0
	s_add_i32 m0, s31, 0x18000
	v_lshl_add_u64 v[42:43], v[42:43], 0, s[50:51]
	s_waitcnt vmcnt(2)
	s_barrier
	global_load_lds_dwordx4 v[42:43], off
	v_lshl_add_u64 v[40:41], v[40:41], 0, s[50:51]
	s_add_i32 m0, s31, 0x1a000
	s_add_i32 s59, s31, 0x8000
	global_load_lds_dwordx4 v[40:41], off
	v_lshl_add_u64 v[36:37], v[36:37], 0, s[50:51]
	s_mov_b32 m0, s59
	s_add_i32 s62, s31, 0xa000
	global_load_lds_dwordx4 v[36:37], off
	v_lshl_add_u64 v[36:37], v[38:39], 0, s[50:51]
	s_mov_b32 m0, s62
	s_add_i32 s64, s31, 0x1c000
	global_load_lds_dwordx4 v[36:37], off
	s_add_i32 s65, s31, 0x1e000
	s_lshl_b32 s4, s6, 13
	s_waitcnt vmcnt(4)
	s_barrier
	v_mbcnt_lo_u32_b32 v1, -1, 0
	v_mbcnt_hi_u32_b32 v1, -1, v1
	v_mov_b32_e32 v106, 0
	v_and_b32_e32 v36, 15, v1
	v_or_b32_e32 v37, s45, v36
	v_ashrrev_i32_e32 v38, 6, v1
	v_lshlrev_b32_e32 v39, 6, v37
	v_and_b32_e32 v40, 48, v1
	v_lshlrev_b32_e32 v37, 2, v37
	v_and_or_b32 v39, v39, s63, v40
	v_lshl_add_u32 v41, v38, 10, s4
	v_and_b32_e32 v37, 32, v37
	s_lshr_b32 s4, s46, 3
	v_lshlrev_b32_e32 v1, 2, v1
	v_bitop3_b32 v37, v39, v41, v37 bitop3:0xde
	v_lshl_or_b32 v36, v36, 6, v40
	v_add_lshl_u32 v38, v38, s4, 10
	v_and_b32_e32 v1, 32, v1
	s_cmp_lt_u32 s9, 4
	v_bitop3_b32 v1, v36, v38, v1 bitop3:0xde
	v_add_u32_e32 v176, 0, v37
	s_cselect_b64 s[18:19], -1, 0
	s_ashr_i32 s67, s0, 31
	s_mov_b32 s9, s49
	s_mov_b32 s13, 0
	s_mov_b32 s68, 1
	s_movk_i32 s69, 0x400
	s_mov_b32 s70, 0
	v_mov_b32_e32 v107, v106
	v_mov_b32_e32 v110, v106
	v_mov_b32_e32 v111, v106
	v_mov_b32_e32 v108, v106
	v_mov_b32_e32 v109, v106
	v_mov_b32_e32 v112, v106
	v_mov_b32_e32 v113, v106
	v_mov_b32_e32 v114, v106
	v_mov_b32_e32 v115, v106
	v_mov_b32_e32 v118, v106
	v_mov_b32_e32 v119, v106
	v_mov_b32_e32 v116, v106
	v_mov_b32_e32 v117, v106
	v_mov_b32_e32 v120, v106
	v_mov_b32_e32 v121, v106
	v_mov_b32_e32 v122, v106
	v_mov_b32_e32 v123, v106
	v_mov_b32_e32 v126, v106
	v_mov_b32_e32 v127, v106
	v_mov_b32_e32 v124, v106
	v_mov_b32_e32 v125, v106
	v_mov_b32_e32 v128, v106
	v_mov_b32_e32 v129, v106
	v_mov_b32_e32 v130, v106
	v_mov_b32_e32 v131, v106
	v_mov_b32_e32 v134, v106
	v_mov_b32_e32 v135, v106
	v_mov_b32_e32 v132, v106
	v_mov_b32_e32 v133, v106
	v_mov_b32_e32 v136, v106
	v_mov_b32_e32 v137, v106
	v_mov_b32_e32 v138, v106
	v_mov_b32_e32 v139, v106
	v_mov_b32_e32 v142, v106
	v_mov_b32_e32 v143, v106
	v_mov_b32_e32 v140, v106
	v_mov_b32_e32 v141, v106
	v_mov_b32_e32 v144, v106
	v_mov_b32_e32 v145, v106
	v_mov_b32_e32 v146, v106
	v_mov_b32_e32 v147, v106
	v_mov_b32_e32 v150, v106
	v_mov_b32_e32 v151, v106
	v_mov_b32_e32 v148, v106
	v_mov_b32_e32 v149, v106
	v_mov_b32_e32 v152, v106
	v_mov_b32_e32 v153, v106
	v_mov_b32_e32 v154, v106
	v_mov_b32_e32 v155, v106
	v_mov_b32_e32 v158, v106
	v_mov_b32_e32 v159, v106
	v_mov_b32_e32 v156, v106
	v_mov_b32_e32 v157, v106
	v_mov_b32_e32 v160, v106
	v_mov_b32_e32 v161, v106
	v_mov_b32_e32 v162, v106
	v_mov_b32_e32 v163, v106
	v_mov_b32_e32 v164, v106
	v_mov_b32_e32 v165, v106
	v_mov_b32_e32 v166, v106
	v_mov_b32_e32 v167, v106
	v_mov_b32_e32 v168, v106
	v_mov_b32_e32 v169, v106
	s_waitcnt vmcnt(0)
	s_branch .LBB0_886

; #define PG8_STAGE(bufoff, gbase, voff) do { _Pragma("unroll") for (int _i = 0; _i < 2; ++_i) \
;         __builtin_amdgcn_global_load_lds((const unsigned*)((const char*)(gbase) + (voff)[_i]), (LAS unsigned*)(lds + (bufoff) + ldsw + _i * 8192), 16, 0, 0); } while (0)
; #define PG8_LDA(dst, b, h) do { _Pragma("unroll") for (int m = 0; m < 4; ++m) _Pragma("unroll") for (int k = 0; k < 2; ++k) dst[m][k] = *(const LAS bf16x8*)(lds + PG8_SA(b, h) + aoff + m * 2048 + k * 1024); } while (0)
; #define PG8_LDB(dst, b, h) do { _Pragma("unroll") for (int n = 0; n < 2; ++n) _Pragma("unroll") for (int k = 0; k < 2; ++k) dst[n][k] = *(const LAS bf16x8*)(lds + PG8_SB(b, h) + boff + n * 2048 + k * 1024); } while (0)
; #define PG8_WAIT_V(n) asm volatile("s_waitcnt vmcnt(" #n ")" ::: "memory")
; #define PG8_WAIT_L(n) asm volatile("s_waitcnt lgkmcnt(" #n ")" ::: "memory")
; template <class Epi, class Sched, bool HALFN = false>
; __device__ __forceinline__ void gemm_phase(LAS unsigned char* lds, const Gemm g, const Sched& S, const Epi& E, int wave_s) {
;     ...
;         const bool has_next = S.next(ui + 1, nxt);
;         const char* nA = has_next ? (const char*)g.A + (size_t)nxt.z * g.zA * 2 + (size_t)nxt.pm * tstep : cA; const char* nB = has_next ? (const char*)g.Bt + (size_t)nxt.z * g.zB * 2 + (size_t)nxt.pn * (HALFN ? hstep : tstep) : cB;
;         for (int t = 0; t < nt; t += 2) {
;             const bool last = (t == nt - 2);
;             const char* a1 = cA + (size_t)(t + 1) * kstep;
;             const char* a2 = last ? nA : cA + (size_t)(t + 2) * kstep; const char* b2 = last ? nB : cB + (size_t)(t + 2) * kstep;
;             const char* a3 = a2 + kstep; const char* b3 = b2 + kstep;
;             PG8_LDB(B0, 0, 0); if (!HALFN) PG8_LDB(B1, 0, 1); PG8_SCHED; PG8_LDA(At, 0, 0); PG8_STAGE(PG8_SA(1, 1), a1 + hstep, voffA);
;             PG8_WAIT_V(8); PG8_WAIT_L(0); PG8_BAR; PG8_MMA(0, 0, At, B0); if (!HALFN) PG8_MMA(0, 1, At, B1); PG8_BAR; PG8_SCHED;
;             PG8_LDA(At, 0, 1); PG8_STAGE(PG8_SB(0, 0), b2, voffB); PG8_STAGE(PG8_SB(0, 1), b2 + bh1, voffB); PG8_STAGE(PG8_SA(0, 0), a2, voffA);
;             PG8_WAIT_V(8); PG8_WAIT_L(0); PG8_BAR; PG8_MMA(1, 0, At, B0); if (!HALFN) PG8_MMA(1, 1, At, B1); PG8_BAR; PG8_SCHED;
;             PG8_LDB(B0, 1, 0); if (!HALFN) PG8_LDB(B1, 1, 1); PG8_SCHED; PG8_LDA(At, 1, 0); PG8_STAGE(PG8_SA(0, 1), a2 + hstep, voffA);
.LBB0_890:
	s_lshl_b64 s[26:27], s[48:49], 20
	s_add_u32 s23, s38, s26
	s_addc_u32 s29, s39, s27
	s_ashr_i32 s21, s20, 31
	s_lshl_b64 s[26:27], s[20:21], 17
	s_add_u32 s26, s23, s26
	s_addc_u32 s27, s29, s27
	s_and_b64 s[4:5], s[4:5], exec
	s_cselect_b32 s5, s27, s37
	s_cselect_b32 s4, s26, s36
	s_add_i32 s48, 0, 0x10000
	v_add_u32_e32 v44, s48, v1
	ds_read_b128 v[46:49], v44
	ds_read_b128 v[50:53], v44 offset:1024
	ds_read_b128 v[54:57], v44 offset:2048
	ds_read_b128 v[58:61], v44 offset:3072
	s_add_u32 s74, s34, 0x20080
	s_addc_u32 s75, s35, 0
	s_add_i32 s52, s31, 0xc000
	v_lshl_add_u64 v[86:87], s[74:75], 0, v[100:101]
	s_mov_b32 m0, s52
	s_add_i32 s21, s31, 0xe000
	ds_read_b128 v[36:39], v176
	ds_read_b128 v[40:43], v176 offset:1024
	ds_read_b128 v[62:65], v176 offset:2048
	ds_read_b128 v[66:69], v176 offset:3072
	ds_read_b128 v[70:73], v176 offset:4096
	ds_read_b128 v[74:77], v176 offset:5120
	ds_read_b128 v[78:81], v176 offset:6144
	ds_read_b128 v[82:85], v176 offset:7168
	global_load_lds_dwordx4 v[86:87], off
	v_lshl_add_u64 v[86:87], s[74:75], 0, v[102:103]
	s_mov_b32 m0, s21
	s_nop 0
	global_load_lds_dwordx4 v[86:87], off
	s_waitcnt vmcnt(14)
	s_waitcnt lgkmcnt(0)
	s_barrier
	s_setprio 1
	s_waitcnt lgkmcnt(0)
	v_mfma_f32_16x16x32_bf16 v[86:89], v[46:49], v[36:39], 0
	v_mfma_f32_16x16x32_bf16 v[36:39], v[54:57], v[36:39], 0
	v_mfma_f32_16x16x32_bf16 v[90:93], v[58:61], v[40:43], v[36:39]
	v_mfma_f32_16x16x32_bf16 v[36:39], v[46:49], v[62:65], 0
	v_mfma_f32_16x16x32_bf16 v[94:97], v[50:53], v[66:69], v[36:39]
	v_mfma_f32_16x16x32_bf16 v[36:39], v[54:57], v[62:65], 0
	v_mfma_f32_16x16x32_bf16 v[62:65], v[58:61], v[66:69], v[36:39]
	v_mfma_f32_16x16x32_bf16 v[36:39], v[46:49], v[70:73], 0
	v_mfma_f32_16x16x32_bf16 v[66:69], v[50:53], v[74:77], v[36:39]
	v_mfma_f32_16x16x32_bf16 v[36:39], v[54:57], v[70:73], 0
	v_mfma_f32_16x16x32_bf16 v[70:73], v[58:61], v[74:77], v[36:39]
	v_mfma_f32_16x16x32_bf16 v[36:39], v[46:49], v[78:81], 0
	v_mfma_f32_16x16x32_bf16 v[74:77], v[50:53], v[82:85], v[36:39]
	v_mfma_f32_16x16x32_bf16 v[36:39], v[54:57], v[78:81], 0
	v_mfma_f32_16x16x32_bf16 v[86:89], v[50:53], v[40:43], v[86:89]
	v_mfma_f32_16x16x32_bf16 v[78:81], v[58:61], v[82:85], v[36:39]
	s_setprio 0
	s_barrier
	s_nop 3
	v_lshl_add_u64 v[36:37], s[36:37], 0, v[18:19]
	s_mov_b64 s[74:75], 0x100
	s_add_i32 s48, s48, s41
	v_lshl_add_u64 v[40:41], v[36:37], 0, s[74:75]
	s_mov_b32 m0, s48
	v_lshl_add_u64 v[38:39], s[36:37], 0, v[104:105]
	s_add_i32 s23, s48, 0x2000
	ds_read_b128 v[82:85], v176 offset:16384
	ds_read_b128 v[170:173], v176 offset:17408
	ds_read_b128 v[178:181], v176 offset:18432
	ds_read_b128 v[182:185], v176 offset:19456
	ds_read_b128 v[186:189], v176 offset:20480
	ds_read_b128 v[190:193], v176 offset:21504
	ds_read_b128 v[194:197], v176 offset:22528
	ds_read_b128 v[208:211], v176 offset:23552
	global_load_lds_dwordx4 v[40:41], off
	v_lshl_add_u64 v[42:43], v[38:39], 0, s[74:75]
	s_mov_b32 m0, s23
	s_nop 0
	global_load_lds_dwordx4 v[42:43], off
	v_lshl_add_u64 v[40:41], s[34:35], 0, v[100:101]
	v_lshl_add_u64 v[42:43], v[40:41], 0, s[74:75]
	s_mov_b32 m0, s31
	s_nop 0
	global_load_lds_dwordx4 v[42:43], off
	v_lshl_add_u64 v[42:43], s[34:35], 0, v[102:103]
	v_lshl_add_u64 v[98:99], v[42:43], 0, s[74:75]
	s_mov_b32 m0, s56
	s_nop 0
	global_load_lds_dwordx4 v[98:99], off
	s_waitcnt vmcnt(14)
	s_waitcnt lgkmcnt(0)
	s_barrier
	s_setprio 1
	s_waitcnt lgkmcnt(0)
	v_mfma_f32_16x16x32_bf16 v[212:215], v[46:49], v[82:85], 0
	v_mfma_f32_16x16x32_bf16 v[82:85], v[54:57], v[82:85], 0
	v_mfma_f32_16x16x32_bf16 v[212:215], v[50:53], v[170:173], v[212:215]
	v_mfma_f32_16x16x32_bf16 v[82:85], v[58:61], v[170:173], v[82:85]
	v_mfma_f32_16x16x32_bf16 v[170:173], v[46:49], v[178:181], 0
	v_mfma_f32_16x16x32_bf16 v[178:181], v[54:57], v[178:181], 0
	v_mfma_f32_16x16x32_bf16 v[170:173], v[50:53], v[182:185], v[170:173]
	v_mfma_f32_16x16x32_bf16 v[178:181], v[58:61], v[182:185], v[178:181]
	v_mfma_f32_16x16x32_bf16 v[182:185], v[46:49], v[186:189], 0
	v_mfma_f32_16x16x32_bf16 v[46:49], v[46:49], v[194:197], 0
	v_mfma_f32_16x16x32_bf16 v[182:185], v[50:53], v[190:193], v[182:185]
	v_mfma_f32_16x16x32_bf16 v[46:49], v[50:53], v[208:211], v[46:49]
	v_mfma_f32_16x16x32_bf16 v[50:53], v[54:57], v[194:197], 0
	v_mfma_f32_16x16x32_bf16 v[186:189], v[54:57], v[186:189], 0
	v_mfma_f32_16x16x32_bf16 v[50:53], v[58:61], v[208:211], v[50:53]
	v_mfma_f32_16x16x32_bf16 v[186:189], v[58:61], v[190:193], v[186:189]
	s_setprio 0
	s_barrier
	s_add_i32 s29, 0, 0x18000
	v_add_u32_e32 v45, s29, v1
	ds_read_b128 v[54:57], v45
	ds_read_b128 v[58:61], v45 offset:1024
	ds_read_b128 v[190:193], v45 offset:2048
	ds_read_b128 v[194:197], v45 offset:3072
	s_add_u32 s36, s34, 0x20100
	s_addc_u32 s37, s35, 0
	s_mov_b32 m0, s57
	v_lshl_add_u64 v[98:99], s[36:37], 0, v[100:101]
	ds_read_b128 v[208:211], v176 offset:32768
	ds_read_b128 v[216:219], v176 offset:33792
	ds_read_b128 v[220:223], v176 offset:34816
	ds_read_b128 v[224:227], v176 offset:35840
	ds_read_b128 v[228:231], v176 offset:36864
	ds_read_b128 v[232:235], v176 offset:37888
	ds_read_b128 v[236:239], v176 offset:38912
	ds_read_b128 v[240:243], v176 offset:39936
	global_load_lds_dwordx4 v[98:99], off
	v_lshl_add_u64 v[98:99], s[36:37], 0, v[102:103]
	s_mov_b32 m0, s58
	s_nop 0
	global_load_lds_dwordx4 v[98:99], off
	s_waitcnt vmcnt(6)
	s_waitcnt lgkmcnt(0)
	s_barrier
; #define PG8_STAGE(bufoff, gbase, voff) do { _Pragma("unroll") for (int _i = 0; _i < 2; ++_i) \
;         __builtin_amdgcn_global_load_lds((const unsigned*)((const char*)(gbase) + (voff)[_i]), (LAS unsigned*)(lds + (bufoff) + ldsw + _i * 8192), 16, 0, 0); } while (0)
; #define PG8_LDA(dst, b, h) do { _Pragma("unroll") for (int m = 0; m < 4; ++m) _Pragma("unroll") for (int k = 0; k < 2; ++k) dst[m][k] = *(const LAS bf16x8*)(lds + PG8_SA(b, h) + aoff + m * 2048 + k * 1024); } while (0)
; #define PG8_LDB(dst, b, h) do { _Pragma("unroll") for (int n = 0; n < 2; ++n) _Pragma("unroll") for (int k = 0; k < 2; ++k) dst[n][k] = *(const LAS bf16x8*)(lds + PG8_SB(b, h) + boff + n * 2048 + k * 1024); } while (0)
; #define PG8_MMA(ai, bj, At, Bt) do { __builtin_amdgcn_s_setprio(1); _Pragma("unroll") for (int m = 0; m < 4; ++m) _Pragma("unroll") for (int n = 0; n < 2; ++n) _Pragma("unroll") for (int k = 0; k < 2; ++k) \
;         acc[ai][bj][m][n] = __builtin_amdgcn_mfma_f32_16x16x32_bf16(Bt[n][k], At[m][k], acc[ai][bj][m][n], 0, 0, 0); __builtin_amdgcn_s_setprio(0); } while (0)
; template <class Epi, class Sched, bool HALFN = false>
; __device__ __forceinline__ void gemm_phase(LAS unsigned char* lds, const Gemm g, const Sched& S, const Epi& E, int wave_s) {
;     ...
;             PG8_LDB(B0, 0, 0); if (!HALFN) PG8_LDB(B1, 0, 1); PG8_SCHED; PG8_LDA(At, 0, 0); PG8_STAGE(PG8_SA(1, 1), a1 + hstep, voffA);
;             PG8_WAIT_V(8); PG8_WAIT_L(0); PG8_BAR; PG8_MMA(0, 0, At, B0); if (!HALFN) PG8_MMA(0, 1, At, B1); PG8_BAR; PG8_SCHED;
;             PG8_LDA(At, 0, 1); PG8_STAGE(PG8_SB(0, 0), b2, voffB); PG8_STAGE(PG8_SB(0, 1), b2 + bh1, voffB); PG8_STAGE(PG8_SA(0, 0), a2, voffA);
;             PG8_WAIT_V(8); PG8_WAIT_L(0); PG8_BAR; PG8_MMA(1, 0, At, B0); if (!HALFN) PG8_MMA(1, 1, At, B1); PG8_BAR; PG8_SCHED;
;             PG8_LDB(B0, 1, 0); if (!HALFN) PG8_LDB(B1, 1, 1); PG8_SCHED; PG8_LDA(At, 1, 0); PG8_STAGE(PG8_SA(0, 1), a2 + hstep, voffA);
;             PG8_WAIT_V(8); PG8_WAIT_L(0); PG8_BAR; PG8_MMA(0, 0, At, B0); if (!HALFN) PG8_MMA(0, 1, At, B1); PG8_BAR; PG8_SCHED;
;             PG8_LDA(At, 1, 1); PG8_STAGE(PG8_SB(1, 0), b3, voffB); PG8_STAGE(PG8_SB(1, 1), b3 + bh1, voffB); PG8_STAGE(PG8_SA(1, 0), a3, voffA);
;             PG8_WAIT_V(8); PG8_WAIT_L(0); PG8_BAR; PG8_MMA(1, 0, At, B0); if (!HALFN) PG8_MMA(1, 1, At, B1); PG8_BAR; PG8_SCHED;
	s_setprio 1
	s_waitcnt lgkmcnt(0)
	v_mfma_f32_16x16x32_bf16 v[86:89], v[54:57], v[208:211], v[86:89]
	v_mfma_f32_16x16x32_bf16 v[90:93], v[190:193], v[208:211], v[90:93]
	v_mfma_f32_16x16x32_bf16 v[94:97], v[54:57], v[220:223], v[94:97]
	v_mfma_f32_16x16x32_bf16 v[62:65], v[190:193], v[220:223], v[62:65]
	v_mfma_f32_16x16x32_bf16 v[66:69], v[54:57], v[228:231], v[66:69]
	v_mfma_f32_16x16x32_bf16 v[70:73], v[190:193], v[228:231], v[70:73]
	v_mfma_f32_16x16x32_bf16 v[74:77], v[54:57], v[236:239], v[74:77]
	v_mfma_f32_16x16x32_bf16 v[78:81], v[190:193], v[236:239], v[78:81]
	v_mfma_f32_16x16x32_bf16 v[86:89], v[58:61], v[216:219], v[86:89]
	v_mfma_f32_16x16x32_bf16 v[90:93], v[194:197], v[216:219], v[90:93]
	v_mfma_f32_16x16x32_bf16 v[94:97], v[58:61], v[224:227], v[94:97]
	v_mfma_f32_16x16x32_bf16 v[62:65], v[194:197], v[224:227], v[62:65]
	v_mfma_f32_16x16x32_bf16 v[66:69], v[58:61], v[232:235], v[66:69]
	v_mfma_f32_16x16x32_bf16 v[70:73], v[194:197], v[232:235], v[70:73]
	v_mfma_f32_16x16x32_bf16 v[74:77], v[58:61], v[240:243], v[74:77]
	v_mfma_f32_16x16x32_bf16 v[78:81], v[194:197], v[240:243], v[78:81]
	s_setprio 0
	s_barrier
	s_mov_b64 s[74:75], 0x180
	s_add_i32 s36, s29, s41
	v_lshl_add_u64 v[98:99], v[36:37], 0, s[74:75]
	s_mov_b32 m0, s36
	s_add_i32 s29, s36, 0x2000
	ds_read_b128 v[208:211], v176 offset:49152
	ds_read_b128 v[216:219], v176 offset:50176
	ds_read_b128 v[220:223], v176 offset:51200
	ds_read_b128 v[224:227], v176 offset:52224
	ds_read_b128 v[228:231], v176 offset:53248
	ds_read_b128 v[232:235], v176 offset:54272
	ds_read_b128 v[236:239], v176 offset:55296
	ds_read_b128 v[240:243], v176 offset:56320
	global_load_lds_dwordx4 v[98:99], off
	v_lshl_add_u64 v[174:175], v[38:39], 0, s[74:75]
	s_mov_b32 m0, s29
	s_nop 0
	global_load_lds_dwordx4 v[174:175], off
	v_lshl_add_u64 v[98:99], v[40:41], 0, s[74:75]
	s_mov_b32 m0, s59
	s_nop 0
	global_load_lds_dwordx4 v[98:99], off
	v_lshl_add_u64 v[98:99], v[42:43], 0, s[74:75]
	s_mov_b32 m0, s62
	s_nop 0
	global_load_lds_dwordx4 v[98:99], off
	s_waitcnt vmcnt(6)
	s_waitcnt lgkmcnt(0)
	s_barrier
	s_setprio 1
	s_waitcnt lgkmcnt(0)
	v_mfma_f32_16x16x32_bf16 v[82:85], v[190:193], v[208:211], v[82:85]
	v_mfma_f32_16x16x32_bf16 v[46:49], v[54:57], v[236:239], v[46:49]
	v_mfma_f32_16x16x32_bf16 v[50:53], v[190:193], v[236:239], v[50:53]
	v_mfma_f32_16x16x32_bf16 v[212:215], v[54:57], v[208:211], v[212:215]
	v_mfma_f32_16x16x32_bf16 v[82:85], v[194:197], v[216:219], v[82:85]
	v_mfma_f32_16x16x32_bf16 v[170:173], v[54:57], v[220:223], v[170:173]
	v_mfma_f32_16x16x32_bf16 v[178:181], v[190:193], v[220:223], v[178:181]
	v_mfma_f32_16x16x32_bf16 v[182:185], v[54:57], v[228:231], v[182:185]
	v_mfma_f32_16x16x32_bf16 v[186:189], v[190:193], v[228:231], v[186:189]
	v_mfma_f32_16x16x32_bf16 v[46:49], v[58:61], v[240:243], v[46:49]
	v_mfma_f32_16x16x32_bf16 v[50:53], v[194:197], v[240:243], v[50:53]
	v_mfma_f32_16x16x32_bf16 v[212:215], v[58:61], v[216:219], v[212:215]
	v_mfma_f32_16x16x32_bf16 v[170:173], v[58:61], v[224:227], v[170:173]
	v_mfma_f32_16x16x32_bf16 v[178:181], v[194:197], v[224:227], v[178:181]
	v_mfma_f32_16x16x32_bf16 v[182:185], v[58:61], v[232:235], v[182:185]
	v_mfma_f32_16x16x32_bf16 v[186:189], v[194:197], v[232:235], v[186:189]
	s_setprio 0
	s_barrier
	ds_read_b128 v[54:57], v44
	ds_read_b128 v[58:61], v44 offset:1024
	ds_read_b128 v[190:193], v44 offset:2048
	ds_read_b128 v[194:197], v44 offset:3072
	s_add_u32 s74, s34, 0x20180
	s_addc_u32 s75, s35, 0
	s_mov_b32 m0, s52
	v_lshl_add_u64 v[98:99], s[74:75], 0, v[100:101]
	ds_read_b128 v[208:211], v176
	ds_read_b128 v[216:219], v176 offset:1024
	ds_read_b128 v[220:223], v176 offset:2048
	ds_read_b128 v[224:227], v176 offset:3072
	ds_read_b128 v[228:231], v176 offset:4096
	ds_read_b128 v[232:235], v176 offset:5120
	ds_read_b128 v[236:239], v176 offset:6144
	ds_read_b128 v[240:243], v176 offset:7168
	global_load_lds_dwordx4 v[98:99], off
	v_lshl_add_u64 v[98:99], s[74:75], 0, v[102:103]
	s_mov_b32 m0, s21
	s_nop 0
	global_load_lds_dwordx4 v[98:99], off
	s_waitcnt vmcnt(6)
	s_waitcnt lgkmcnt(0)
	s_barrier
	s_setprio 1
	s_waitcnt lgkmcnt(0)
	v_mfma_f32_16x16x32_bf16 v[86:89], v[54:57], v[208:211], v[86:89]
	v_mfma_f32_16x16x32_bf16 v[90:93], v[190:193], v[208:211], v[90:93]
	v_mfma_f32_16x16x32_bf16 v[94:97], v[54:57], v[220:223], v[94:97]
	v_mfma_f32_16x16x32_bf16 v[62:65], v[190:193], v[220:223], v[62:65]
	v_mfma_f32_16x16x32_bf16 v[66:69], v[54:57], v[228:231], v[66:69]
	v_mfma_f32_16x16x32_bf16 v[70:73], v[190:193], v[228:231], v[70:73]
	v_mfma_f32_16x16x32_bf16 v[74:77], v[54:57], v[236:239], v[74:77]
	v_mfma_f32_16x16x32_bf16 v[78:81], v[190:193], v[236:239], v[78:81]
	v_mfma_f32_16x16x32_bf16 v[86:89], v[58:61], v[216:219], v[86:89]
	v_mfma_f32_16x16x32_bf16 v[90:93], v[194:197], v[216:219], v[90:93]
	v_mfma_f32_16x16x32_bf16 v[94:97], v[58:61], v[224:227], v[94:97]
	v_mfma_f32_16x16x32_bf16 v[62:65], v[194:197], v[224:227], v[62:65]
	v_mfma_f32_16x16x32_bf16 v[66:69], v[58:61], v[232:235], v[66:69]
	v_mfma_f32_16x16x32_bf16 v[70:73], v[194:197], v[232:235], v[70:73]
	v_mfma_f32_16x16x32_bf16 v[74:77], v[58:61], v[240:243], v[74:77]
	v_mfma_f32_16x16x32_bf16 v[78:81], v[194:197], v[240:243], v[78:81]
	s_setprio 0
	s_barrier
; #define PG8_STAGE(bufoff, gbase, voff) do { _Pragma("unroll") for (int _i = 0; _i < 2; ++_i) \
;         __builtin_amdgcn_global_load_lds((const unsigned*)((const char*)(gbase) + (voff)[_i]), (LAS unsigned*)(lds + (bufoff) + ldsw + _i * 8192), 16, 0, 0); } while (0)
; #define PG8_LDA(dst, b, h) do { _Pragma("unroll") for (int m = 0; m < 4; ++m) _Pragma("unroll") for (int k = 0; k < 2; ++k) dst[m][k] = *(const LAS bf16x8*)(lds + PG8_SA(b, h) + aoff + m * 2048 + k * 1024); } while (0)
; #define PG8_LDB(dst, b, h) do { _Pragma("unroll") for (int n = 0; n < 2; ++n) _Pragma("unroll") for (int k = 0; k < 2; ++k) dst[n][k] = *(const LAS bf16x8*)(lds + PG8_SB(b, h) + boff + n * 2048 + k * 1024); } while (0)
; #define PG8_MMA(ai, bj, At, Bt) do { __builtin_amdgcn_s_setprio(1); _Pragma("unroll") for (int m = 0; m < 4; ++m) _Pragma("unroll") for (int n = 0; n < 2; ++n) _Pragma("unroll") for (int k = 0; k < 2; ++k) \
;         acc[ai][bj][m][n] = __builtin_amdgcn_mfma_f32_16x16x32_bf16(Bt[n][k], At[m][k], acc[ai][bj][m][n], 0, 0, 0); __builtin_amdgcn_s_setprio(0); } while (0)
; template <class Epi, class Sched, bool HALFN = false>
; __device__ __forceinline__ void gemm_phase(LAS unsigned char* lds, const Gemm g, const Sched& S, const Epi& E, int wave_s) {
;     ...
;             PG8_LDB(B0, 0, 0); if (!HALFN) PG8_LDB(B1, 0, 1); PG8_SCHED; PG8_LDA(At, 0, 0); PG8_STAGE(PG8_SA(1, 1), a1 + hstep, voffA);
;             PG8_WAIT_V(8); PG8_WAIT_L(0); PG8_BAR; PG8_MMA(0, 0, At, B0); if (!HALFN) PG8_MMA(0, 1, At, B1); PG8_BAR; PG8_SCHED;
;             PG8_LDA(At, 0, 1); PG8_STAGE(PG8_SB(0, 0), b2, voffB); PG8_STAGE(PG8_SB(0, 1), b2 + bh1, voffB); PG8_STAGE(PG8_SA(0, 0), a2, voffA);
;             PG8_WAIT_V(8); PG8_WAIT_L(0); PG8_BAR; PG8_MMA(1, 0, At, B0); if (!HALFN) PG8_MMA(1, 1, At, B1); PG8_BAR; PG8_SCHED;
;             PG8_LDB(B0, 1, 0); if (!HALFN) PG8_LDB(B1, 1, 1); PG8_SCHED; PG8_LDA(At, 1, 0); PG8_STAGE(PG8_SA(0, 1), a2 + hstep, voffA);
;             PG8_WAIT_V(8); PG8_WAIT_L(0); PG8_BAR; PG8_MMA(0, 0, At, B0); if (!HALFN) PG8_MMA(0, 1, At, B1); PG8_BAR; PG8_SCHED;
;             PG8_LDA(At, 1, 1); PG8_STAGE(PG8_SB(1, 0), b3, voffB); PG8_STAGE(PG8_SB(1, 1), b3 + bh1, voffB); PG8_STAGE(PG8_SA(1, 0), a3, voffA);
;             PG8_WAIT_V(8); PG8_WAIT_L(0); PG8_BAR; PG8_MMA(1, 0, At, B0); if (!HALFN) PG8_MMA(1, 1, At, B1); PG8_BAR; PG8_SCHED;
	s_mov_b64 s[74:75], 0x200
	s_mov_b32 m0, s48
	v_lshl_add_u64 v[98:99], v[36:37], 0, s[74:75]
	ds_read_b128 v[208:211], v176 offset:16384
	ds_read_b128 v[216:219], v176 offset:17408
	ds_read_b128 v[220:223], v176 offset:18432
	ds_read_b128 v[224:227], v176 offset:19456
	ds_read_b128 v[228:231], v176 offset:20480
	ds_read_b128 v[232:235], v176 offset:21504
	ds_read_b128 v[236:239], v176 offset:22528
	ds_read_b128 v[240:243], v176 offset:23552
	global_load_lds_dwordx4 v[98:99], off
	v_lshl_add_u64 v[174:175], v[38:39], 0, s[74:75]
	s_mov_b32 m0, s23
	s_nop 0
	global_load_lds_dwordx4 v[174:175], off
	v_lshl_add_u64 v[98:99], v[40:41], 0, s[74:75]
	s_mov_b32 m0, s31
	s_nop 0
	global_load_lds_dwordx4 v[98:99], off
	v_lshl_add_u64 v[98:99], v[42:43], 0, s[74:75]
	s_mov_b32 m0, s56
	s_nop 0
	global_load_lds_dwordx4 v[98:99], off
	s_waitcnt vmcnt(6)
	s_waitcnt lgkmcnt(0)
	s_barrier
	s_setprio 1
	s_waitcnt lgkmcnt(0)
	v_mfma_f32_16x16x32_bf16 v[82:85], v[190:193], v[208:211], v[82:85]
	v_mfma_f32_16x16x32_bf16 v[46:49], v[54:57], v[236:239], v[46:49]
	v_mfma_f32_16x16x32_bf16 v[50:53], v[190:193], v[236:239], v[50:53]
	v_mfma_f32_16x16x32_bf16 v[212:215], v[54:57], v[208:211], v[212:215]
	v_mfma_f32_16x16x32_bf16 v[82:85], v[194:197], v[216:219], v[82:85]
	v_mfma_f32_16x16x32_bf16 v[170:173], v[54:57], v[220:223], v[170:173]
	v_mfma_f32_16x16x32_bf16 v[178:181], v[190:193], v[220:223], v[178:181]
	v_mfma_f32_16x16x32_bf16 v[182:185], v[54:57], v[228:231], v[182:185]
	v_mfma_f32_16x16x32_bf16 v[186:189], v[190:193], v[228:231], v[186:189]
	v_mfma_f32_16x16x32_bf16 v[46:49], v[58:61], v[240:243], v[46:49]
	v_mfma_f32_16x16x32_bf16 v[50:53], v[194:197], v[240:243], v[50:53]
	v_mfma_f32_16x16x32_bf16 v[212:215], v[58:61], v[216:219], v[212:215]
	v_mfma_f32_16x16x32_bf16 v[170:173], v[58:61], v[224:227], v[170:173]
	v_mfma_f32_16x16x32_bf16 v[178:181], v[194:197], v[224:227], v[178:181]
	v_mfma_f32_16x16x32_bf16 v[182:185], v[58:61], v[232:235], v[182:185]
	v_mfma_f32_16x16x32_bf16 v[186:189], v[194:197], v[232:235], v[186:189]
	s_setprio 0
	s_barrier
	ds_read_b128 v[54:57], v45
	ds_read_b128 v[58:61], v45 offset:1024
	ds_read_b128 v[190:193], v45 offset:2048
	ds_read_b128 v[194:197], v45 offset:3072
	s_add_u32 s74, s34, 0x20200
	s_addc_u32 s75, s35, 0
	s_mov_b32 m0, s57
	v_lshl_add_u64 v[98:99], s[74:75], 0, v[100:101]
	ds_read_b128 v[208:211], v176 offset:32768
	ds_read_b128 v[216:219], v176 offset:33792
	ds_read_b128 v[220:223], v176 offset:34816
	ds_read_b128 v[224:227], v176 offset:35840
	ds_read_b128 v[228:231], v176 offset:36864
	ds_read_b128 v[232:235], v176 offset:37888
	ds_read_b128 v[236:239], v176 offset:38912
	ds_read_b128 v[240:243], v176 offset:39936
	global_load_lds_dwordx4 v[98:99], off
	v_lshl_add_u64 v[98:99], s[74:75], 0, v[102:103]
	s_mov_b32 m0, s58
	s_nop 0
	global_load_lds_dwordx4 v[98:99], off
	s_waitcnt vmcnt(6)
	s_waitcnt lgkmcnt(0)
	s_barrier
	s_setprio 1
	s_waitcnt lgkmcnt(0)
	v_mfma_f32_16x16x32_bf16 v[86:89], v[54:57], v[208:211], v[86:89]
	v_mfma_f32_16x16x32_bf16 v[90:93], v[190:193], v[208:211], v[90:93]
	v_mfma_f32_16x16x32_bf16 v[94:97], v[54:57], v[220:223], v[94:97]
	v_mfma_f32_16x16x32_bf16 v[62:65], v[190:193], v[220:223], v[62:65]
	v_mfma_f32_16x16x32_bf16 v[66:69], v[54:57], v[228:231], v[66:69]
	v_mfma_f32_16x16x32_bf16 v[70:73], v[190:193], v[228:231], v[70:73]
	v_mfma_f32_16x16x32_bf16 v[74:77], v[54:57], v[236:239], v[74:77]
	v_mfma_f32_16x16x32_bf16 v[78:81], v[190:193], v[236:239], v[78:81]
	v_mfma_f32_16x16x32_bf16 v[86:89], v[58:61], v[216:219], v[86:89]
	v_mfma_f32_16x16x32_bf16 v[90:93], v[194:197], v[216:219], v[90:93]
	v_mfma_f32_16x16x32_bf16 v[94:97], v[58:61], v[224:227], v[94:97]
	v_mfma_f32_16x16x32_bf16 v[62:65], v[194:197], v[224:227], v[62:65]
	v_mfma_f32_16x16x32_bf16 v[66:69], v[58:61], v[232:235], v[66:69]
	v_mfma_f32_16x16x32_bf16 v[70:73], v[194:197], v[232:235], v[70:73]
	v_mfma_f32_16x16x32_bf16 v[74:77], v[58:61], v[240:243], v[74:77]
	v_mfma_f32_16x16x32_bf16 v[78:81], v[194:197], v[240:243], v[78:81]
	s_setprio 0
	s_barrier
	s_mov_b64 s[74:75], 0x280
	s_mov_b32 m0, s36
	v_lshl_add_u64 v[98:99], v[36:37], 0, s[74:75]
	ds_read_b128 v[208:211], v176 offset:49152
	ds_read_b128 v[216:219], v176 offset:50176
	ds_read_b128 v[220:223], v176 offset:51200
	ds_read_b128 v[224:227], v176 offset:52224
	ds_read_b128 v[228:231], v176 offset:53248
	ds_read_b128 v[232:235], v176 offset:54272
	ds_read_b128 v[236:239], v176 offset:55296
	ds_read_b128 v[240:243], v176 offset:56320
	global_load_lds_dwordx4 v[98:99], off
	v_lshl_add_u64 v[174:175], v[38:39], 0, s[74:75]
	s_mov_b32 m0, s29
	s_nop 0
	global_load_lds_dwordx4 v[174:175], off
	v_lshl_add_u64 v[98:99], v[40:41], 0, s[74:75]
	s_mov_b32 m0, s59
	s_nop 0
	global_load_lds_dwordx4 v[98:99], off
	v_lshl_add_u64 v[98:99], v[42:43], 0, s[74:75]
	s_mov_b32 m0, s62
	s_nop 0
	global_load_lds_dwordx4 v[98:99], off
	s_waitcnt vmcnt(6)
	s_waitcnt lgkmcnt(0)
	s_barrier
	s_setprio 1
	s_waitcnt lgkmcnt(0)
	v_mfma_f32_16x16x32_bf16 v[82:85], v[190:193], v[208:211], v[82:85]
	v_mfma_f32_16x16x32_bf16 v[46:49], v[54:57], v[236:239], v[46:49]
	v_mfma_f32_16x16x32_bf16 v[50:53], v[190:193], v[236:239], v[50:53]
	v_mfma_f32_16x16x32_bf16 v[212:215], v[54:57], v[208:211], v[212:215]
	v_mfma_f32_16x16x32_bf16 v[82:85], v[194:197], v[216:219], v[82:85]
	v_mfma_f32_16x16x32_bf16 v[170:173], v[54:57], v[220:223], v[170:173]
	v_mfma_f32_16x16x32_bf16 v[178:181], v[190:193], v[220:223], v[178:181]
	v_mfma_f32_16x16x32_bf16 v[182:185], v[54:57], v[228:231], v[182:185]
	v_mfma_f32_16x16x32_bf16 v[186:189], v[190:193], v[228:231], v[186:189]
	v_mfma_f32_16x16x32_bf16 v[46:49], v[58:61], v[240:243], v[46:49]
	v_mfma_f32_16x16x32_bf16 v[50:53], v[194:197], v[240:243], v[50:53]
	v_mfma_f32_16x16x32_bf16 v[212:215], v[58:61], v[216:219], v[212:215]
	v_mfma_f32_16x16x32_bf16 v[170:173], v[58:61], v[224:227], v[170:173]
	v_mfma_f32_16x16x32_bf16 v[178:181], v[194:197], v[224:227], v[178:181]
	v_mfma_f32_16x16x32_bf16 v[182:185], v[58:61], v[232:235], v[182:185]
	v_mfma_f32_16x16x32_bf16 v[186:189], v[194:197], v[232:235], v[186:189]
	s_setprio 0
	s_barrier
; #define PG8_STAGE(bufoff, gbase, voff) do { _Pragma("unroll") for (int _i = 0; _i < 2; ++_i) \
;         __builtin_amdgcn_global_load_lds((const unsigned*)((const char*)(gbase) + (voff)[_i]), (LAS unsigned*)(lds + (bufoff) + ldsw + _i * 8192), 16, 0, 0); } while (0)
; #define PG8_LDA(dst, b, h) do { _Pragma("unroll") for (int m = 0; m < 4; ++m) _Pragma("unroll") for (int k = 0; k < 2; ++k) dst[m][k] = *(const LAS bf16x8*)(lds + PG8_SA(b, h) + aoff + m * 2048 + k * 1024); } while (0)
; #define PG8_LDB(dst, b, h) do { _Pragma("unroll") for (int n = 0; n < 2; ++n) _Pragma("unroll") for (int k = 0; k < 2; ++k) dst[n][k] = *(const LAS bf16x8*)(lds + PG8_SB(b, h) + boff + n * 2048 + k * 1024); } while (0)
; #define PG8_MMA(ai, bj, At, Bt) do { __builtin_amdgcn_s_setprio(1); _Pragma("unroll") for (int m = 0; m < 4; ++m) _Pragma("unroll") for (int n = 0; n < 2; ++n) _Pragma("unroll") for (int k = 0; k < 2; ++k) \
;         acc[ai][bj][m][n] = __builtin_amdgcn_mfma_f32_16x16x32_bf16(Bt[n][k], At[m][k], acc[ai][bj][m][n], 0, 0, 0); __builtin_amdgcn_s_setprio(0); } while (0)
; template <class Epi, class Sched, bool HALFN = false>
; __device__ __forceinline__ void gemm_phase(LAS unsigned char* lds, const Gemm g, const Sched& S, const Epi& E, int wave_s) {
;     ...
;             PG8_LDB(B0, 0, 0); if (!HALFN) PG8_LDB(B1, 0, 1); PG8_SCHED; PG8_LDA(At, 0, 0); PG8_STAGE(PG8_SA(1, 1), a1 + hstep, voffA);
;             PG8_WAIT_V(8); PG8_WAIT_L(0); PG8_BAR; PG8_MMA(0, 0, At, B0); if (!HALFN) PG8_MMA(0, 1, At, B1); PG8_BAR; PG8_SCHED;
;             PG8_LDA(At, 0, 1); PG8_STAGE(PG8_SB(0, 0), b2, voffB); PG8_STAGE(PG8_SB(0, 1), b2 + bh1, voffB); PG8_STAGE(PG8_SA(0, 0), a2, voffA);
;             PG8_WAIT_V(8); PG8_WAIT_L(0); PG8_BAR; PG8_MMA(1, 0, At, B0); if (!HALFN) PG8_MMA(1, 1, At, B1); PG8_BAR; PG8_SCHED;
;             PG8_LDB(B0, 1, 0); if (!HALFN) PG8_LDB(B1, 1, 1); PG8_SCHED; PG8_LDA(At, 1, 0); PG8_STAGE(PG8_SA(0, 1), a2 + hstep, voffA);
;             PG8_WAIT_V(8); PG8_WAIT_L(0); PG8_BAR; PG8_MMA(0, 0, At, B0); if (!HALFN) PG8_MMA(0, 1, At, B1); PG8_BAR; PG8_SCHED;
;             PG8_LDA(At, 1, 1); PG8_STAGE(PG8_SB(1, 0), b3, voffB); PG8_STAGE(PG8_SB(1, 1), b3 + bh1, voffB); PG8_STAGE(PG8_SA(1, 0), a3, voffA);
;             PG8_WAIT_V(8); PG8_WAIT_L(0); PG8_BAR; PG8_MMA(1, 0, At, B0); if (!HALFN) PG8_MMA(1, 1, At, B1); PG8_BAR; PG8_SCHED;
	ds_read_b128 v[54:57], v44
	ds_read_b128 v[58:61], v44 offset:1024
	ds_read_b128 v[190:193], v44 offset:2048
	ds_read_b128 v[194:197], v44 offset:3072
	s_add_u32 s74, s34, 0x20280
	s_addc_u32 s75, s35, 0
	s_mov_b32 m0, s52
	v_lshl_add_u64 v[98:99], s[74:75], 0, v[100:101]
	ds_read_b128 v[208:211], v176
	ds_read_b128 v[216:219], v176 offset:1024
	ds_read_b128 v[220:223], v176 offset:2048
	ds_read_b128 v[224:227], v176 offset:3072
	ds_read_b128 v[228:231], v176 offset:4096
	ds_read_b128 v[232:235], v176 offset:5120
	ds_read_b128 v[236:239], v176 offset:6144
	ds_read_b128 v[240:243], v176 offset:7168
	global_load_lds_dwordx4 v[98:99], off
	v_lshl_add_u64 v[98:99], s[74:75], 0, v[102:103]
	s_mov_b32 m0, s21
	s_nop 0
	global_load_lds_dwordx4 v[98:99], off
	s_waitcnt vmcnt(6)
	s_waitcnt lgkmcnt(0)
	s_barrier
	s_setprio 1
	s_waitcnt lgkmcnt(0)
	v_mfma_f32_16x16x32_bf16 v[86:89], v[54:57], v[208:211], v[86:89]
	v_mfma_f32_16x16x32_bf16 v[90:93], v[190:193], v[208:211], v[90:93]
	v_mfma_f32_16x16x32_bf16 v[94:97], v[54:57], v[220:223], v[94:97]
	v_mfma_f32_16x16x32_bf16 v[62:65], v[190:193], v[220:223], v[62:65]
	v_mfma_f32_16x16x32_bf16 v[66:69], v[54:57], v[228:231], v[66:69]
	v_mfma_f32_16x16x32_bf16 v[70:73], v[190:193], v[228:231], v[70:73]
	v_mfma_f32_16x16x32_bf16 v[74:77], v[54:57], v[236:239], v[74:77]
	v_mfma_f32_16x16x32_bf16 v[78:81], v[190:193], v[236:239], v[78:81]
	v_mfma_f32_16x16x32_bf16 v[86:89], v[58:61], v[216:219], v[86:89]
	v_mfma_f32_16x16x32_bf16 v[90:93], v[194:197], v[216:219], v[90:93]
	v_mfma_f32_16x16x32_bf16 v[94:97], v[58:61], v[224:227], v[94:97]
	v_mfma_f32_16x16x32_bf16 v[62:65], v[194:197], v[224:227], v[62:65]
	v_mfma_f32_16x16x32_bf16 v[66:69], v[58:61], v[232:235], v[66:69]
	v_mfma_f32_16x16x32_bf16 v[70:73], v[194:197], v[232:235], v[70:73]
	v_mfma_f32_16x16x32_bf16 v[74:77], v[58:61], v[240:243], v[74:77]
	v_mfma_f32_16x16x32_bf16 v[78:81], v[194:197], v[240:243], v[78:81]
	s_setprio 0
	s_barrier
	s_mov_b64 s[74:75], 0x300
	s_mov_b32 m0, s48
	v_lshl_add_u64 v[98:99], v[36:37], 0, s[74:75]
	ds_read_b128 v[208:211], v176 offset:16384
	ds_read_b128 v[216:219], v176 offset:17408
	ds_read_b128 v[220:223], v176 offset:18432
	ds_read_b128 v[224:227], v176 offset:19456
	ds_read_b128 v[228:231], v176 offset:20480
	ds_read_b128 v[232:235], v176 offset:21504
	ds_read_b128 v[236:239], v176 offset:22528
	ds_read_b128 v[240:243], v176 offset:23552
	global_load_lds_dwordx4 v[98:99], off
	v_lshl_add_u64 v[174:175], v[38:39], 0, s[74:75]
	s_mov_b32 m0, s23
	s_nop 0
	global_load_lds_dwordx4 v[174:175], off
	v_lshl_add_u64 v[98:99], v[40:41], 0, s[74:75]
	s_mov_b32 m0, s31
	s_nop 0
	global_load_lds_dwordx4 v[98:99], off
	v_lshl_add_u64 v[98:99], v[42:43], 0, s[74:75]
	s_mov_b32 m0, s56
	s_nop 0
	global_load_lds_dwordx4 v[98:99], off
	s_waitcnt vmcnt(6)
	s_waitcnt lgkmcnt(0)
	s_barrier
	s_setprio 1
	s_waitcnt lgkmcnt(0)
	v_mfma_f32_16x16x32_bf16 v[82:85], v[190:193], v[208:211], v[82:85]
	v_mfma_f32_16x16x32_bf16 v[46:49], v[54:57], v[236:239], v[46:49]
	v_mfma_f32_16x16x32_bf16 v[50:53], v[190:193], v[236:239], v[50:53]
	v_mfma_f32_16x16x32_bf16 v[212:215], v[54:57], v[208:211], v[212:215]
	v_mfma_f32_16x16x32_bf16 v[82:85], v[194:197], v[216:219], v[82:85]
	v_mfma_f32_16x16x32_bf16 v[170:173], v[54:57], v[220:223], v[170:173]
	v_mfma_f32_16x16x32_bf16 v[178:181], v[190:193], v[220:223], v[178:181]
	v_mfma_f32_16x16x32_bf16 v[182:185], v[54:57], v[228:231], v[182:185]
	v_mfma_f32_16x16x32_bf16 v[186:189], v[190:193], v[228:231], v[186:189]
	v_mfma_f32_16x16x32_bf16 v[46:49], v[58:61], v[240:243], v[46:49]
	v_mfma_f32_16x16x32_bf16 v[50:53], v[194:197], v[240:243], v[50:53]
	v_mfma_f32_16x16x32_bf16 v[212:215], v[58:61], v[216:219], v[212:215]
	v_mfma_f32_16x16x32_bf16 v[170:173], v[58:61], v[224:227], v[170:173]
	v_mfma_f32_16x16x32_bf16 v[178:181], v[194:197], v[224:227], v[178:181]
	v_mfma_f32_16x16x32_bf16 v[182:185], v[58:61], v[232:235], v[182:185]
	v_mfma_f32_16x16x32_bf16 v[186:189], v[194:197], v[232:235], v[186:189]
	s_setprio 0
	s_barrier
	ds_read_b128 v[54:57], v45
	ds_read_b128 v[58:61], v45 offset:1024
	ds_read_b128 v[190:193], v45 offset:2048
	ds_read_b128 v[194:197], v45 offset:3072
	s_add_u32 s74, s34, 0x20300
	s_addc_u32 s75, s35, 0
	s_mov_b32 m0, s57
	v_lshl_add_u64 v[98:99], s[74:75], 0, v[100:101]
	ds_read_b128 v[208:211], v176 offset:32768
	ds_read_b128 v[216:219], v176 offset:33792
	ds_read_b128 v[220:223], v176 offset:34816
	ds_read_b128 v[224:227], v176 offset:35840
	ds_read_b128 v[228:231], v176 offset:36864
	ds_read_b128 v[232:235], v176 offset:37888
	ds_read_b128 v[236:239], v176 offset:38912
	ds_read_b128 v[240:243], v176 offset:39936
	global_load_lds_dwordx4 v[98:99], off
	v_lshl_add_u64 v[98:99], s[74:75], 0, v[102:103]
	s_mov_b32 m0, s58
	s_nop 0
	global_load_lds_dwordx4 v[98:99], off
	s_waitcnt vmcnt(6)
	s_waitcnt lgkmcnt(0)
	s_barrier
	s_setprio 1
	s_waitcnt lgkmcnt(0)
	v_mfma_f32_16x16x32_bf16 v[86:89], v[54:57], v[208:211], v[86:89]
	v_mfma_f32_16x16x32_bf16 v[90:93], v[190:193], v[208:211], v[90:93]
	v_mfma_f32_16x16x32_bf16 v[94:97], v[54:57], v[220:223], v[94:97]
	v_mfma_f32_16x16x32_bf16 v[62:65], v[190:193], v[220:223], v[62:65]
	v_mfma_f32_16x16x32_bf16 v[66:69], v[54:57], v[228:231], v[66:69]
	v_mfma_f32_16x16x32_bf16 v[70:73], v[190:193], v[228:231], v[70:73]
	v_mfma_f32_16x16x32_bf16 v[74:77], v[54:57], v[236:239], v[74:77]
	v_mfma_f32_16x16x32_bf16 v[78:81], v[190:193], v[236:239], v[78:81]
	v_mfma_f32_16x16x32_bf16 v[86:89], v[58:61], v[216:219], v[86:89]
	v_mfma_f32_16x16x32_bf16 v[90:93], v[194:197], v[216:219], v[90:93]
	v_mfma_f32_16x16x32_bf16 v[94:97], v[58:61], v[224:227], v[94:97]
	v_mfma_f32_16x16x32_bf16 v[62:65], v[194:197], v[224:227], v[62:65]
	v_mfma_f32_16x16x32_bf16 v[66:69], v[58:61], v[232:235], v[66:69]
	v_mfma_f32_16x16x32_bf16 v[70:73], v[194:197], v[232:235], v[70:73]
	v_mfma_f32_16x16x32_bf16 v[74:77], v[58:61], v[240:243], v[74:77]
	v_mfma_f32_16x16x32_bf16 v[78:81], v[194:197], v[240:243], v[78:81]
	s_setprio 0
	s_barrier
; #define PG8_STAGE(bufoff, gbase, voff) do { _Pragma("unroll") for (int _i = 0; _i < 2; ++_i) \
;         __builtin_amdgcn_global_load_lds((const unsigned*)((const char*)(gbase) + (voff)[_i]), (LAS unsigned*)(lds + (bufoff) + ldsw + _i * 8192), 16, 0, 0); } while (0)
; #define PG8_LDA(dst, b, h) do { _Pragma("unroll") for (int m = 0; m < 4; ++m) _Pragma("unroll") for (int k = 0; k < 2; ++k) dst[m][k] = *(const LAS bf16x8*)(lds + PG8_SA(b, h) + aoff + m * 2048 + k * 1024); } while (0)
; #define PG8_LDB(dst, b, h) do { _Pragma("unroll") for (int n = 0; n < 2; ++n) _Pragma("unroll") for (int k = 0; k < 2; ++k) dst[n][k] = *(const LAS bf16x8*)(lds + PG8_SB(b, h) + boff + n * 2048 + k * 1024); } while (0)
; #define PG8_WAIT_V(n) asm volatile("s_waitcnt vmcnt(" #n ")" ::: "memory")
; #define PG8_WAIT_L(n) asm volatile("s_waitcnt lgkmcnt(" #n ")" ::: "memory")
; #define PG8_BAR __builtin_amdgcn_s_barrier()
; template <class Epi, class Sched, bool HALFN = false>
; __device__ __forceinline__ void gemm_phase(LAS unsigned char* lds, const Gemm g, const Sched& S, const Epi& E, int wave_s) {
;     ...
;             const char* a2 = last ? nA : cA + (size_t)(t + 2) * kstep; const char* b2 = last ? nB : cB + (size_t)(t + 2) * kstep;
;             const char* a3 = a2 + kstep; const char* b3 = b2 + kstep;
;             PG8_LDB(B0, 0, 0); if (!HALFN) PG8_LDB(B1, 0, 1); PG8_SCHED; PG8_LDA(At, 0, 0); PG8_STAGE(PG8_SA(1, 1), a1 + hstep, voffA);
;             PG8_WAIT_V(8); PG8_WAIT_L(0); PG8_BAR; PG8_MMA(0, 0, At, B0); if (!HALFN) PG8_MMA(0, 1, At, B1); PG8_BAR; PG8_SCHED;
;             PG8_LDA(At, 0, 1); PG8_STAGE(PG8_SB(0, 0), b2, voffB); PG8_STAGE(PG8_SB(0, 1), b2 + bh1, voffB); PG8_STAGE(PG8_SA(0, 0), a2, voffA);
;             PG8_WAIT_V(8); PG8_WAIT_L(0); PG8_BAR; PG8_MMA(1, 0, At, B0); if (!HALFN) PG8_MMA(1, 1, At, B1); PG8_BAR; PG8_SCHED;
;             PG8_LDB(B0, 1, 0); if (!HALFN) PG8_LDB(B1, 1, 1); PG8_SCHED; PG8_LDA(At, 1, 0); PG8_STAGE(PG8_SA(0, 1), a2 + hstep, voffA);
;             PG8_WAIT_V(8); PG8_WAIT_L(0); PG8_BAR; PG8_MMA(0, 0, At, B0); if (!HALFN) PG8_MMA(0, 1, At, B1); PG8_BAR; PG8_SCHED;
;             PG8_LDA(At, 1, 1); PG8_STAGE(PG8_SB(1, 0), b3, voffB); PG8_STAGE(PG8_SB(1, 1), b3 + bh1, voffB); PG8_STAGE(PG8_SA(1, 0), a3, voffA);
;             PG8_WAIT_V(8); PG8_WAIT_L(0); PG8_BAR; PG8_MMA(1, 0, At, B0); if (!HALFN) PG8_MMA(1, 1, At, B1); PG8_BAR; PG8_SCHED;
	s_mov_b64 s[74:75], 0x380
	s_mov_b32 m0, s36
	v_lshl_add_u64 v[36:37], v[36:37], 0, s[74:75]
	ds_read_b128 v[208:211], v176 offset:49152
	ds_read_b128 v[216:219], v176 offset:50176
	ds_read_b128 v[220:223], v176 offset:51200
	ds_read_b128 v[224:227], v176 offset:52224
	ds_read_b128 v[228:231], v176 offset:53248
	ds_read_b128 v[232:235], v176 offset:54272
	ds_read_b128 v[236:239], v176 offset:55296
	ds_read_b128 v[240:243], v176 offset:56320
	global_load_lds_dwordx4 v[36:37], off
	v_lshl_add_u64 v[38:39], v[38:39], 0, s[74:75]
	s_mov_b32 m0, s29
	s_nop 0
	global_load_lds_dwordx4 v[38:39], off
	v_lshl_add_u64 v[36:37], v[40:41], 0, s[74:75]
	s_mov_b32 m0, s59
	s_nop 0
	global_load_lds_dwordx4 v[36:37], off
	v_lshl_add_u64 v[36:37], v[42:43], 0, s[74:75]
	s_mov_b32 m0, s62
	s_nop 0
	global_load_lds_dwordx4 v[36:37], off
	s_waitcnt vmcnt(6)
	s_waitcnt lgkmcnt(0)
	s_barrier
	s_setprio 1
	s_waitcnt lgkmcnt(0)
	v_mfma_f32_16x16x32_bf16 v[36:39], v[54:57], v[208:211], v[212:215]
	v_mfma_f32_16x16x32_bf16 v[40:43], v[190:193], v[208:211], v[82:85]
	v_mfma_f32_16x16x32_bf16 v[82:85], v[54:57], v[220:223], v[170:173]
	v_mfma_f32_16x16x32_bf16 v[46:49], v[54:57], v[236:239], v[46:49]
	v_mfma_f32_16x16x32_bf16 v[50:53], v[190:193], v[236:239], v[50:53]
	v_mfma_f32_16x16x32_bf16 v[36:39], v[58:61], v[216:219], v[36:39]
	v_mfma_f32_16x16x32_bf16 v[40:43], v[194:197], v[216:219], v[40:43]
	v_mfma_f32_16x16x32_bf16 v[82:85], v[58:61], v[224:227], v[82:85]
	v_mfma_f32_16x16x32_bf16 v[170:173], v[190:193], v[220:223], v[178:181]
	v_mfma_f32_16x16x32_bf16 v[178:181], v[54:57], v[228:231], v[182:185]
	v_mfma_f32_16x16x32_bf16 v[182:185], v[190:193], v[228:231], v[186:189]
	v_mfma_f32_16x16x32_bf16 v[46:49], v[58:61], v[240:243], v[46:49]
	v_mfma_f32_16x16x32_bf16 v[50:53], v[194:197], v[240:243], v[50:53]
	v_mfma_f32_16x16x32_bf16 v[170:173], v[194:197], v[224:227], v[170:173]
	v_mfma_f32_16x16x32_bf16 v[178:181], v[58:61], v[232:235], v[178:181]
	v_mfma_f32_16x16x32_bf16 v[182:185], v[194:197], v[232:235], v[182:185]
	s_setprio 0
	s_barrier
	ds_read_b128 v[54:57], v44
	ds_read_b128 v[58:61], v44 offset:1024
	ds_read_b128 v[186:189], v44 offset:2048
	ds_read_b128 v[190:193], v44 offset:3072
	s_add_u32 s34, s34, 0x20380
	s_addc_u32 s35, s35, 0
	s_mov_b32 m0, s52
	v_lshl_add_u64 v[98:99], s[34:35], 0, v[100:101]
	ds_read_b128 v[194:197], v176
	ds_read_b128 v[208:211], v176 offset:1024
	ds_read_b128 v[212:215], v176 offset:2048
	ds_read_b128 v[216:219], v176 offset:3072
	ds_read_b128 v[220:223], v176 offset:4096
	ds_read_b128 v[224:227], v176 offset:5120
	ds_read_b128 v[228:231], v176 offset:6144
	ds_read_b128 v[232:235], v176 offset:7168
	global_load_lds_dwordx4 v[98:99], off
	v_lshl_add_u64 v[98:99], s[34:35], 0, v[102:103]
	s_mov_b32 m0, s21
	s_nop 0
	global_load_lds_dwordx4 v[98:99], off
	s_waitcnt vmcnt(6)
	s_waitcnt lgkmcnt(0)
	s_barrier
	s_setprio 1
	s_waitcnt lgkmcnt(0)
	v_mfma_f32_16x16x32_bf16 v[86:89], v[54:57], v[194:197], v[86:89]
	v_mfma_f32_16x16x32_bf16 v[90:93], v[186:189], v[194:197], v[90:93]
	v_mfma_f32_16x16x32_bf16 v[62:65], v[186:189], v[212:215], v[62:65]
	v_mfma_f32_16x16x32_bf16 v[66:69], v[54:57], v[220:223], v[66:69]
	v_mfma_f32_16x16x32_bf16 v[70:73], v[186:189], v[220:223], v[70:73]
	v_mfma_f32_16x16x32_bf16 v[74:77], v[54:57], v[228:231], v[74:77]
	v_mfma_f32_16x16x32_bf16 v[86:89], v[58:61], v[208:211], v[86:89]
	v_mfma_f32_16x16x32_bf16 v[90:93], v[190:193], v[208:211], v[90:93]
	v_mfma_f32_16x16x32_bf16 v[94:97], v[54:57], v[212:215], v[94:97]
	v_mfma_f32_16x16x32_bf16 v[62:65], v[190:193], v[216:219], v[62:65]
	v_mfma_f32_16x16x32_bf16 v[66:69], v[58:61], v[224:227], v[66:69]
	v_mfma_f32_16x16x32_bf16 v[70:73], v[190:193], v[224:227], v[70:73]
	v_mfma_f32_16x16x32_bf16 v[208:211], v[58:61], v[232:235], v[74:77]
	v_mfma_f32_16x16x32_bf16 v[74:77], v[186:189], v[228:231], v[78:81]
	v_mfma_f32_16x16x32_bf16 v[194:197], v[58:61], v[216:219], v[94:97]
	v_mfma_f32_16x16x32_bf16 v[212:215], v[190:193], v[232:235], v[74:77]
	s_setprio 0
	s_barrier
	s_mov_b32 m0, s48
	v_lshl_add_u64 v[174:175], s[4:5], 0, v[18:19]
	s_nop 1
	ds_read_b128 v[74:77], v176 offset:16384
	ds_read_b128 v[78:81], v176 offset:17408
	ds_read_b128 v[94:97], v176 offset:18432
	ds_read_b128 v[216:219], v176 offset:19456
	ds_read_b128 v[220:223], v176 offset:20480
	ds_read_b128 v[224:227], v176 offset:21504
	ds_read_b128 v[228:231], v176 offset:22528
	ds_read_b128 v[232:235], v176 offset:23552
	global_load_lds_dwordx4 v[174:175], off
	v_lshl_add_u64 v[198:199], s[4:5], 0, v[104:105]
	s_mov_b32 m0, s23
	v_lshl_add_u64 v[202:203], s[24:25], 0, v[100:101]
	global_load_lds_dwordx4 v[198:199], off
	v_lshl_add_u64 v[248:249], s[24:25], 0, v[102:103]
	s_mov_b32 m0, s31
	s_nop 0
	global_load_lds_dwordx4 v[202:203], off
	s_mov_b32 m0, s56
	s_nop 0
	global_load_lds_dwordx4 v[248:249], off
	s_waitcnt vmcnt(6)
	s_waitcnt lgkmcnt(0)
	s_barrier
; #define PG8_STAGE(bufoff, gbase, voff) do { _Pragma("unroll") for (int _i = 0; _i < 2; ++_i) \
;         __builtin_amdgcn_global_load_lds((const unsigned*)((const char*)(gbase) + (voff)[_i]), (LAS unsigned*)(lds + (bufoff) + ldsw + _i * 8192), 16, 0, 0); } while (0)
; #define PG8_LDA(dst, b, h) do { _Pragma("unroll") for (int m = 0; m < 4; ++m) _Pragma("unroll") for (int k = 0; k < 2; ++k) dst[m][k] = *(const LAS bf16x8*)(lds + PG8_SA(b, h) + aoff + m * 2048 + k * 1024); } while (0)
; #define PG8_LDB(dst, b, h) do { _Pragma("unroll") for (int n = 0; n < 2; ++n) _Pragma("unroll") for (int k = 0; k < 2; ++k) dst[n][k] = *(const LAS bf16x8*)(lds + PG8_SB(b, h) + boff + n * 2048 + k * 1024); } while (0)
; #define PG8_WAIT_V(n) asm volatile("s_waitcnt vmcnt(" #n ")" ::: "memory")
; #define PG8_WAIT_L(n) asm volatile("s_waitcnt lgkmcnt(" #n ")" ::: "memory")
; template <class Epi, class Sched, bool HALFN = false>
; __device__ __forceinline__ void gemm_phase(LAS unsigned char* lds, const Gemm g, const Sched& S, const Epi& E, int wave_s) {
;     ...
;             const char* a2 = last ? nA : cA + (size_t)(t + 2) * kstep; const char* b2 = last ? nB : cB + (size_t)(t + 2) * kstep;
;             const char* a3 = a2 + kstep; const char* b3 = b2 + kstep;
;             PG8_LDB(B0, 0, 0); if (!HALFN) PG8_LDB(B1, 0, 1); PG8_SCHED; PG8_LDA(At, 0, 0); PG8_STAGE(PG8_SA(1, 1), a1 + hstep, voffA);
;             PG8_WAIT_V(8); PG8_WAIT_L(0); PG8_BAR; PG8_MMA(0, 0, At, B0); if (!HALFN) PG8_MMA(0, 1, At, B1); PG8_BAR; PG8_SCHED;
;             PG8_LDA(At, 0, 1); PG8_STAGE(PG8_SB(0, 0), b2, voffB); PG8_STAGE(PG8_SB(0, 1), b2 + bh1, voffB); PG8_STAGE(PG8_SA(0, 0), a2, voffA);
;             PG8_WAIT_V(8); PG8_WAIT_L(0); PG8_BAR; PG8_MMA(1, 0, At, B0); if (!HALFN) PG8_MMA(1, 1, At, B1); PG8_BAR; PG8_SCHED;
;             PG8_LDB(B0, 1, 0); if (!HALFN) PG8_LDB(B1, 1, 1); PG8_SCHED; PG8_LDA(At, 1, 0); PG8_STAGE(PG8_SA(0, 1), a2 + hstep, voffA);
;             PG8_WAIT_V(8); PG8_WAIT_L(0); PG8_BAR; PG8_MMA(0, 0, At, B0); if (!HALFN) PG8_MMA(0, 1, At, B1); PG8_BAR; PG8_SCHED;
;             PG8_LDA(At, 1, 1); PG8_STAGE(PG8_SB(1, 0), b3, voffB); PG8_STAGE(PG8_SB(1, 1), b3 + bh1, voffB); PG8_STAGE(PG8_SA(1, 0), a3, voffA);
;             PG8_WAIT_V(8); PG8_WAIT_L(0); PG8_BAR; PG8_MMA(1, 0, At, B0); if (!HALFN) PG8_MMA(1, 1, At, B1); PG8_BAR; PG8_SCHED;
;         }
;         if (wr == 0) PG8_BAR;
	s_setprio 1
	s_waitcnt lgkmcnt(0)
	v_mfma_f32_16x16x32_bf16 v[36:39], v[54:57], v[74:77], v[36:39]
	v_mfma_f32_16x16x32_bf16 v[40:43], v[186:189], v[74:77], v[40:43]
	v_mfma_f32_16x16x32_bf16 v[74:77], v[54:57], v[94:97], v[82:85]
	v_mfma_f32_16x16x32_bf16 v[236:239], v[58:61], v[216:219], v[74:77]
	v_mfma_f32_16x16x32_bf16 v[74:77], v[186:189], v[94:97], v[170:173]
	v_mfma_f32_16x16x32_bf16 v[170:173], v[190:193], v[216:219], v[74:77]
	v_mfma_f32_16x16x32_bf16 v[74:77], v[54:57], v[220:223], v[178:181]
	v_mfma_f32_16x16x32_bf16 v[46:49], v[54:57], v[228:231], v[46:49]
	v_mfma_f32_16x16x32_bf16 v[36:39], v[58:61], v[78:81], v[36:39]
	v_mfma_f32_16x16x32_bf16 v[40:43], v[190:193], v[78:81], v[40:43]
	v_mfma_f32_16x16x32_bf16 v[178:181], v[58:61], v[224:227], v[74:77]
	v_mfma_f32_16x16x32_bf16 v[74:77], v[186:189], v[220:223], v[182:185]
	v_mfma_f32_16x16x32_bf16 v[216:219], v[58:61], v[232:235], v[46:49]
	v_mfma_f32_16x16x32_bf16 v[46:49], v[186:189], v[228:231], v[50:53]
	v_mfma_f32_16x16x32_bf16 v[182:185], v[190:193], v[224:227], v[74:77]
	v_mfma_f32_16x16x32_bf16 v[186:189], v[190:193], v[232:235], v[46:49]
	s_setprio 0
	s_barrier
	ds_read_b128 v[190:193], v45
	ds_read_b128 v[220:223], v45 offset:1024
	ds_read_b128 v[224:227], v45 offset:2048
	ds_read_b128 v[228:231], v45 offset:3072
	s_add_u32 s4, s24, 0x20000
	s_addc_u32 s5, s25, 0
	s_mov_b32 m0, s57
	v_lshl_add_u64 v[60:61], s[4:5], 0, v[100:101]
	ds_read_b128 v[44:47], v176 offset:32768
	ds_read_b128 v[48:51], v176 offset:33792
	ds_read_b128 v[52:55], v176 offset:34816
	ds_read_b128 v[56:59], v176 offset:35840
	ds_read_b128 v[74:77], v176 offset:36864
	ds_read_b128 v[232:235], v176 offset:37888
	ds_read_b128 v[240:243], v176 offset:38912
	ds_read_b128 v[244:247], v176 offset:39936
	global_load_lds_dwordx4 v[60:61], off
	v_lshl_add_u64 v[60:61], s[4:5], 0, v[102:103]
	s_mov_b32 m0, s58
	s_nop 0
	global_load_lds_dwordx4 v[60:61], off
	s_waitcnt vmcnt(6)
	s_waitcnt lgkmcnt(0)
	s_barrier
	s_setprio 1
	s_waitcnt lgkmcnt(0)
	v_mfma_f32_16x16x32_bf16 v[78:81], v[190:193], v[44:47], v[86:89]
	v_mfma_f32_16x16x32_bf16 v[44:47], v[224:227], v[44:47], v[90:93]
	v_mfma_f32_16x16x32_bf16 v[92:95], v[228:231], v[48:51], v[44:47]
	v_mfma_f32_16x16x32_bf16 v[44:47], v[190:193], v[52:55], v[194:197]
	v_mfma_f32_16x16x32_bf16 v[88:91], v[220:223], v[56:59], v[44:47]
	v_mfma_f32_16x16x32_bf16 v[44:47], v[224:227], v[52:55], v[62:65]
	v_mfma_f32_16x16x32_bf16 v[84:87], v[228:231], v[56:59], v[44:47]
	v_mfma_f32_16x16x32_bf16 v[44:47], v[190:193], v[74:77], v[66:69]
	v_mfma_f32_16x16x32_bf16 v[96:99], v[220:223], v[48:51], v[78:81]
	v_mfma_f32_16x16x32_bf16 v[80:83], v[220:223], v[232:235], v[44:47]
	v_mfma_f32_16x16x32_bf16 v[44:47], v[224:227], v[74:77], v[70:73]
	v_mfma_f32_16x16x32_bf16 v[76:79], v[228:231], v[232:235], v[44:47]
	v_mfma_f32_16x16x32_bf16 v[44:47], v[190:193], v[240:243], v[208:211]
	v_mfma_f32_16x16x32_bf16 v[72:75], v[220:223], v[244:247], v[44:47]
	v_mfma_f32_16x16x32_bf16 v[44:47], v[224:227], v[240:243], v[212:215]
	v_mfma_f32_16x16x32_bf16 v[68:71], v[228:231], v[244:247], v[44:47]
	s_setprio 0
	s_barrier
	s_mov_b32 m0, s36
	v_lshl_add_u64 v[56:57], v[174:175], 0, s[50:51]
	s_nop 2
	ds_read_b128 v[44:47], v176 offset:49152
	ds_read_b128 v[48:51], v176 offset:50176
	ds_read_b128 v[52:55], v176 offset:51200
	ds_read_b128 v[194:197], v176 offset:52224
	ds_read_b128 v[208:211], v176 offset:53248
	ds_read_b128 v[212:215], v176 offset:54272
	ds_read_b128 v[232:235], v176 offset:55296
	ds_read_b128 v[240:243], v176 offset:56320
	global_load_lds_dwordx4 v[56:57], off
	v_lshl_add_u64 v[58:59], v[198:199], 0, s[50:51]
	s_mov_b32 m0, s29
	s_nop 0
	global_load_lds_dwordx4 v[58:59], off
	v_lshl_add_u64 v[56:57], v[202:203], 0, s[50:51]
	s_mov_b32 m0, s59
	s_nop 0
	global_load_lds_dwordx4 v[56:57], off
	v_lshl_add_u64 v[56:57], v[248:249], 0, s[50:51]
	s_mov_b32 m0, s62
	s_nop 0
	global_load_lds_dwordx4 v[56:57], off
	s_waitcnt vmcnt(6)
	s_waitcnt lgkmcnt(0)
	s_barrier
	s_setprio 1
	s_waitcnt lgkmcnt(0)
	v_mfma_f32_16x16x32_bf16 v[36:39], v[190:193], v[44:47], v[36:39]
	v_mfma_f32_16x16x32_bf16 v[64:67], v[220:223], v[48:51], v[36:39]
	v_mfma_f32_16x16x32_bf16 v[36:39], v[224:227], v[44:47], v[40:43]
	v_mfma_f32_16x16x32_bf16 v[60:63], v[228:231], v[48:51], v[36:39]
	v_mfma_f32_16x16x32_bf16 v[36:39], v[190:193], v[52:55], v[236:239]
	v_mfma_f32_16x16x32_bf16 v[56:59], v[220:223], v[194:197], v[36:39]
	v_mfma_f32_16x16x32_bf16 v[36:39], v[224:227], v[52:55], v[170:173]
	v_mfma_f32_16x16x32_bf16 v[52:55], v[228:231], v[194:197], v[36:39]
	v_mfma_f32_16x16x32_bf16 v[36:39], v[190:193], v[208:211], v[178:181]
	v_mfma_f32_16x16x32_bf16 v[48:51], v[220:223], v[212:215], v[36:39]
	v_mfma_f32_16x16x32_bf16 v[36:39], v[224:227], v[208:211], v[182:185]
	v_mfma_f32_16x16x32_bf16 v[44:47], v[228:231], v[212:215], v[36:39]
	v_mfma_f32_16x16x32_bf16 v[36:39], v[190:193], v[232:235], v[216:219]
	v_mfma_f32_16x16x32_bf16 v[40:43], v[220:223], v[240:243], v[36:39]
	v_mfma_f32_16x16x32_bf16 v[36:39], v[224:227], v[232:235], v[186:189]
	v_mfma_f32_16x16x32_bf16 v[36:39], v[228:231], v[240:243], v[36:39]
	s_setprio 0
	s_barrier
	s_andn2_b64 vcc, exec, s[18:19]
	s_cbranch_vccnz .LBB0_892
	s_barrier
